# NSA tile stream: per-lane fetch/commit address math hoisted out of the loop into otherwise unused VGPRs (-27 VALU per tile per wave)
# speedup vs baseline: 1.0105x; 1.0105x over previous
; DI int otid() { int t = threadIdx.x; asm volatile("" : "+v"(t)); return t; }
; DI u32x4 tile_fetch(const bf16_t* __restrict__ src, size_t stride) {
;   const int c = otid(), row = c >> 3, col = (c & 7) * 8;
;   return *(const u32x4*)&src[(size_t)row * stride + col];
; }
; DI void tile_commit(bf16_t* dst, const u32x4& v) {
;   const int c = otid(), row = c >> 3, col = (c & 7) * 8;
;   *(u32x4*)&dst[row * LDT + col] = v;
; }
; DI void nsa_item(const bf16_t* __restrict__ P, const bf16_t* __restrict__ KC, const bf16_t* __restrict__ VCT,
;                  const bf16_t* __restrict__ VTS, const bf16_t* __restrict__ VTW, bf16_t* __restrict__ Y, int item, char* lds) {
;   const int tid = otid(), lane = tid & 63, wave = tid >> 6, l32 = lane & 31, hh = lane >> 5;
;   const int xq = (item >> 4) & 15, rnd = item >> 8;
;   const int qb = rnd == 0 ? 63 - xq : (rnd == 1 ? xq : (rnd == 2 ? 47 - xq : 16 + xq));
.LBB0_866:
	v_lshrrev_b32_e32 v214, 3, v167
	v_and_b32_e32 v219, 7, v167
	v_lshlrev_b32_e32 v216, 13, v214
	v_mul_lo_u32 v218, v214, s92
	v_mul_u32_u24_e32 v214, 0x1700, v214
	v_lshlrev_b32_e32 v219, 4, v219
	v_mov_b32_e32 v215, 0
	v_mov_b32_e32 v217, 0
	v_add_u32_e32 v214, v214, v219
	v_add_u32_e32 v216, v216, v219
	v_add_u32_e32 v218, v218, v219
	s_waitcnt vmcnt(0)
	v_mov_b32_e32 v81, v167
	s_cmpk_gt_u32 s2, 0xff
	s_mov_b64 s[0:1], -1
	s_cbranch_scc0 .LBB0_868
	s_bfe_u32 s1, s2, 0x40004
	s_ashr_i32 s0, s2, 8
	s_xor_b32 s6, s1, 47
	s_or_b32 s7, s1, 16
	s_cmp_eq_u32 s0, 2
	s_cselect_b32 s6, s6, s7
	s_cmp_eq_u32 s0, 1
	s_cselect_b32 s6, s1, s6
	s_mov_b64 s[0:1], 0

; DI void nsa_item(const bf16_t* __restrict__ P, const bf16_t* __restrict__ KC, const bf16_t* __restrict__ VCT,
;                  const bf16_t* __restrict__ VTS, const bf16_t* __restrict__ VTW, bf16_t* __restrict__ Y, int item, char* lds) {
;     ...
;     auto advance = [&]() {
;       if (sk == 0) { if (rem) { si = __builtin_ctzll(rem); rem &= rem - 1; } else { sk = 1; si = kbs; } }
;       else if (sk == 1) { if (si < cur) ++si; else sk = 2; }
;     };
;     ...
;       const bf16_t* bcur = Ks + par * (4 * TS);
;       bf16_t* bnxt = Ks + (par ^ 1) * (4 * TS);
;       tile_commit(bnxt, pfk); tile_commit(bnxt + TS, pfv); tile_commit(bnxt + 2 * TS, pfk1); tile_commit(bnxt + 3 * TS, pfv1);
;       advance(); const int kc0 = sk, ic0 = si; advance(); const int kc1 = sk, ic1 = si;
.LBB0_929:
	s_xor_b32 s8, s91, 1
	s_mul_i32 s0, s8, 0x9000
	s_cmp_lt_i32 s84, 1
	v_add_u32_e32 v0, s0, v218
	s_waitcnt vmcnt(3)
	ds_write_b128 v0, v[128:131]
	s_waitcnt vmcnt(2)
	ds_write_b128 v0, v[132:135] offset:9216
	s_waitcnt vmcnt(1)
	ds_write_b128 v0, v[136:139] offset:18432
	s_mov_b64 s[0:1], -1
	s_waitcnt vmcnt(0)
	ds_write_b128 v0, v[140:143] offset:27648
	s_cbranch_scc1 .LBB0_937
	s_cmp_eq_u32 s84, 1
	s_mov_b32 s85, s87
	s_mov_b32 s9, s84
	s_cbranch_scc0 .LBB0_932
	s_cmp_lt_i32 s87, s6
	s_cselect_b64 s[0:1], -1, 0
	s_and_b64 s[12:13], s[0:1], exec
	s_cselect_b32 s9, 1, 2
	s_cmp_lg_u64 s[0:1], 0
	s_addc_u32 s85, s87, 0

; DI int crow(int reg, int hh) { return (reg & 3) + 8 * (reg >> 2) + 4 * hh; }
; template <bool HAS_O, class MaskF>
; DI void softmax_step(f32x16 (&S)[2], float& m, float& l, f32x16 (&O)[2], int hh, MaskF mask) {
;   float mx = -1e30f;
; #pragma unroll
;   for (int kt2 = 0; kt2 < 2; ++kt2)
; #pragma unroll
;     for (int e = 0; e < 16; ++e) {
;       const float sv = mask(kt2 * 32 + crow(e, hh)) ? S[kt2][e] : -1e30f;
;       S[kt2][e] = sv; mx = fmaxf(mx, sv);
;     }
; DI void nsa_item(const bf16_t* __restrict__ P, const bf16_t* __restrict__ KC, const bf16_t* __restrict__ VCT,
;                  const bf16_t* __restrict__ VTS, const bf16_t* __restrict__ VTW, bf16_t* __restrict__ Y, int item, char* lds) {
;     ...
;     auto fetch1 = [&](int kd, int ix, u32x4& rk, u32x4& rv) {
;       const int iv = kd < 2 ? ix : 0;
;       const bf16_t* kp = (kd == 0 ? ks0 : kw0) + (size_t)iv * 64 * LDP_E;
;       const bf16_t* vp = (kd == 0 ? vs0 : vw0) + iv * 64;
;       rk = tile_fetch(kp, LDP_E); rv = tile_fetch(vp, SEQ);
;     };
;     auto do_tile = [&](int kd, int ix, const bf16_t* kbuf, int knext) {
;       qk_tile(kbuf, qf, S, l32, hh);
;       if (kd == 0) {
;         const bool mine = (mym >> ix) & 1ull;
;         if (ix < cur) softmax_fast<true>(S, m, l, O, mine);
;         else softmax_step<true>(S, m, l, O, hh, [&](int kk) { return mine && (ix * 64 + kk <= pos); });
;       } else {
;         if (ix < cur && ix > cur - 8) softmax_fast<true>(S, m, l, O, true);
;         else softmax_step<true>(S, m, l, O, hh, [&](int kk) { const int kp = ix * 64 + kk; return kp <= pos && kp > pos - 512; });
.LBB0_945:
	s_cmp_eq_u32 s9, 0
	s_cselect_b32 s1, s45, s48
	s_cselect_b32 s0, s44, s47
	s_cselect_b32 s11, s46, s50
	s_cselect_b32 s14, s7, s49
	s_cmp_lt_i32 s9, 2
	s_cselect_b32 s12, s85, 0
	s_mul_i32 s15, s12, 0x5c000
	s_mul_hi_i32 s13, s12, 0x5c000
	s_add_u32 s0, s0, s15
	s_addc_u32 s1, s1, s13
	v_lshl_add_u64 v[2:3], s[0:1], 0, v[214:215]
	s_lshl_b32 s12, s12, 6
	s_ashr_i32 s13, s12, 31
	s_lshl_b64 s[12:13], s[12:13], 1
	s_add_u32 s12, s14, s12
	s_addc_u32 s13, s11, s13
	global_load_dwordx4 v[128:131], v[2:3], off
	v_lshl_add_u64 v[2:3], s[12:13], 0, v[216:217]
	global_load_dwordx4 v[132:135], v[2:3], off
	s_cmp_eq_u32 s84, 0
	s_cselect_b32 s1, s45, s48
	s_cselect_b32 s0, s44, s47
	s_cselect_b32 s11, s46, s50
	s_cselect_b32 s14, s7, s49
	s_cmp_lt_i32 s84, 2
	s_cselect_b32 s12, s87, 0
	s_mul_i32 s15, s12, 0x5c000
	s_mul_hi_i32 s13, s12, 0x5c000
	s_add_u32 s0, s0, s15
	s_addc_u32 s1, s1, s13
	v_lshl_add_u64 v[2:3], s[0:1], 0, v[214:215]
	s_lshl_b32 s12, s12, 6
	s_ashr_i32 s13, s12, 31
	s_lshl_b64 s[12:13], s[12:13], 1
	global_load_dwordx4 v[136:139], v[2:3], off
	s_add_u32 s12, s14, s12
	s_addc_u32 s13, s11, s13
	v_lshl_add_u64 v[2:3], s[12:13], 0, v[216:217]
	global_load_dwordx4 v[140:143], v[2:3], off
	v_mov_b32_e32 v0, v219
	s_mul_i32 s11, s91, 0x9000
	v_lshl_add_u32 v210, v152, 1, s11
	ds_read_b128 v[2:5], v210
	ds_read_b128 v[6:9], v210 offset:32
	ds_read_b128 v[10:13], v210 offset:64
	ds_read_b128 v[80:83], v210 offset:96
	ds_read_b128 v[48:51], v210 offset:4608
	ds_read_b128 v[84:87], v210 offset:4640
	ds_read_b128 v[88:91], v210 offset:4672
	ds_read_b128 v[92:95], v210 offset:4704
	s_setprio 1
	s_waitcnt lgkmcnt(7)
	v_mfma_f32_32x32x16_bf16 v[64:79], v[2:5], v[112:115], 0
	s_waitcnt lgkmcnt(3)
	v_mfma_f32_32x32x16_bf16 v[48:63], v[48:51], v[112:115], 0
	v_mfma_f32_32x32x16_bf16 v[64:79], v[6:9], v[116:119], v[64:79]
	s_waitcnt lgkmcnt(2)
	v_mfma_f32_32x32x16_bf16 v[48:63], v[84:87], v[116:119], v[48:63]
	v_mfma_f32_32x32x16_bf16 v[64:79], v[10:13], v[120:123], v[64:79]
	s_waitcnt lgkmcnt(1)
	v_mfma_f32_32x32x16_bf16 v[48:63], v[88:91], v[120:123], v[48:63]
	v_mfma_f32_32x32x16_bf16 v[64:79], v[80:83], v[124:127], v[64:79]
	s_waitcnt lgkmcnt(0)
	v_mfma_f32_32x32x16_bf16 v[48:63], v[92:95], v[124:127], v[48:63]
	s_setprio 0
	s_cmp_eq_u32 s86, 0
	s_cselect_b64 s[34:35], -1, 0
	s_cmp_lg_u32 s86, 0
	s_cbranch_scc0 .LBB0_948
	s_cmp_lt_i32 s57, s6
	s_cselect_b64 s[0:1], -1, 0
	s_cmp_gt_i32 s57, s28
	s_cselect_b64 s[12:13], -1, 0
	s_and_b64 s[0:1], s[0:1], s[12:13]
	s_andn2_b64 vcc, exec, s[0:1]
	s_cbranch_vccz .LBB0_949
	s_lshl_b32 s12, s57, 6
	v_or_b32_e32 v0, s12, v153
	v_cmp_le_i32_e32 vcc, v0, v148
	v_cmp_gt_i32_e64 s[0:1], v0, v160
	s_and_b64 vcc, vcc, s[0:1]
	v_cndmask_b32_e32 v2, v185, v64, vcc
	v_cmp_lt_i32_e32 vcc, v0, v148
	v_cmp_ge_i32_e64 s[0:1], v0, v160
	s_and_b64 vcc, vcc, s[0:1]
	v_or_b32_e32 v5, s12, v161
	v_cndmask_b32_e32 v3, v185, v65, vcc
	v_cmp_le_i32_e32 vcc, v5, v148
	v_cmp_gt_i32_e64 s[0:1], v5, v160
	s_and_b64 vcc, vcc, s[0:1]
	v_or_b32_e32 v6, s12, v163
	v_cndmask_b32_e32 v5, v185, v66, vcc
	v_cmp_le_i32_e32 vcc, v6, v148
	v_cmp_gt_i32_e64 s[0:1], v6, v160
	s_and_b64 vcc, vcc, s[0:1]
	v_or_b32_e32 v7, 8, v0
	v_cndmask_b32_e32 v6, v185, v67, vcc
	v_cmp_le_i32_e32 vcc, v7, v148
	v_cmp_gt_i32_e64 s[0:1], v7, v160
	s_and_b64 vcc, vcc, s[0:1]
	v_or_b32_e32 v8, 9, v0
	v_cndmask_b32_e32 v7, v185, v68, vcc
	v_cmp_le_i32_e32 vcc, v8, v148
	v_cmp_gt_i32_e64 s[0:1], v8, v160
	s_and_b64 vcc, vcc, s[0:1]
	v_or_b32_e32 v9, 10, v0
	v_cndmask_b32_e32 v8, v185, v69, vcc
	v_cmp_le_i32_e32 vcc, v9, v148
	v_cmp_gt_i32_e64 s[0:1], v9, v160
	s_and_b64 vcc, vcc, s[0:1]
	v_or_b32_e32 v10, 11, v0
	v_cndmask_b32_e32 v9, v185, v70, vcc
	v_cmp_le_i32_e32 vcc, v10, v148
	v_cmp_gt_i32_e64 s[0:1], v10, v160
	s_and_b64 vcc, vcc, s[0:1]
	v_or_b32_e32 v11, 16, v0
	v_cndmask_b32_e32 v10, v185, v71, vcc
	v_cmp_le_i32_e32 vcc, v11, v148
	v_cmp_gt_i32_e64 s[0:1], v11, v160
	s_and_b64 vcc, vcc, s[0:1]
	v_or_b32_e32 v12, 17, v0
	v_cndmask_b32_e32 v11, v185, v72, vcc
	v_cmp_le_i32_e32 vcc, v12, v148
	v_cmp_gt_i32_e64 s[0:1], v12, v160
	s_and_b64 vcc, vcc, s[0:1]
	v_or_b32_e32 v13, 18, v0
	v_cndmask_b32_e32 v12, v185, v73, vcc
	v_cmp_le_i32_e32 vcc, v13, v148
	v_cmp_gt_i32_e64 s[0:1], v13, v160
	s_and_b64 vcc, vcc, s[0:1]
	v_or_b32_e32 v14, 19, v0
	v_cndmask_b32_e32 v13, v185, v74, vcc
	v_cmp_le_i32_e32 vcc, v14, v148
	v_cmp_gt_i32_e64 s[0:1], v14, v160
	s_and_b64 vcc, vcc, s[0:1]
	v_or_b32_e32 v15, 24, v0
	v_cndmask_b32_e32 v14, v185, v75, vcc
	v_cmp_le_i32_e32 vcc, v15, v148
	v_cmp_gt_i32_e64 s[0:1], v15, v160
	s_and_b64 vcc, vcc, s[0:1]
	v_or_b32_e32 v80, 25, v0
	v_cndmask_b32_e32 v15, v185, v76, vcc
	v_cmp_le_i32_e32 vcc, v80, v148
	v_cmp_gt_i32_e64 s[0:1], v80, v160
	s_and_b64 vcc, vcc, s[0:1]
	v_or_b32_e32 v80, 26, v0
	v_cndmask_b32_e32 v93, v185, v77, vcc
	v_cmp_le_i32_e32 vcc, v80, v148
	v_cmp_gt_i32_e64 s[0:1], v80, v160
	s_and_b64 vcc, vcc, s[0:1]
	v_or_b32_e32 v80, 27, v0
	v_cndmask_b32_e32 v94, v185, v78, vcc
	v_cmp_le_i32_e32 vcc, v80, v148
	v_cmp_gt_i32_e64 s[0:1], v80, v160
	s_and_b64 vcc, vcc, s[0:1]
	v_or_b32_e32 v80, s12, v158
	v_cndmask_b32_e32 v95, v185, v79, vcc
	v_cmp_le_i32_e32 vcc, v80, v148
	v_cmp_gt_i32_e64 s[0:1], v80, v160
	s_and_b64 vcc, vcc, s[0:1]
	v_or_b32_e32 v80, 33, v0
	v_cndmask_b32_e32 v96, v185, v48, vcc
	v_cmp_le_i32_e32 vcc, v80, v148
	v_cmp_gt_i32_e64 s[0:1], v80, v160
	s_and_b64 vcc, vcc, s[0:1]
	v_or_b32_e32 v80, s12, v164
	v_cndmask_b32_e32 v97, v185, v49, vcc
	v_cmp_le_i32_e32 vcc, v80, v148
	v_cmp_gt_i32_e64 s[0:1], v80, v160
	s_and_b64 vcc, vcc, s[0:1]
; DI float half_max(float x) { float a, b; half_swap(x, a, b); return fmaxf(a, b); }
; DI int crow(int reg, int hh) { return (reg & 3) + 8 * (reg >> 2) + 4 * hh; }
; DI float ex2(float x) { return __builtin_amdgcn_exp2f(x); }
; template <bool HAS_O>
; DI void softmax_finish(f32x16 (&S)[2], float mx, float cbias, float& m, float& l, f32x16 (&O)[2]) {
;   mx = half_max(mx);
;   const float mn = (mx > m + 8.f) ? mx : m;
;   const float alpha = ex2(m - mn);
;   m = mn;
;   const float c = mn + cbias;
;   float sum = 0.f;
; #pragma unroll
;   for (int kt2 = 0; kt2 < 2; ++kt2)
; #pragma unroll
;     for (int e = 0; e < 16; ++e) { const float pv = ex2(S[kt2][e] - c); S[kt2][e] = pv; sum += pv; }
;   l = l * alpha + sum;
;   if constexpr (HAS_O) {
;     if (__ballot(alpha != 1.f) != 0ull) {
; #pragma unroll
;       for (int dt = 0; dt < 2; ++dt)
; #pragma unroll
;         for (int e = 0; e < 16; ++e) O[dt][e] *= alpha;
;     }
;   }
; }
; template <bool HAS_O, class MaskF>
; DI void softmax_step(f32x16 (&S)[2], float& m, float& l, f32x16 (&O)[2], int hh, MaskF mask) {
;   float mx = -1e30f;
; #pragma unroll
;   for (int kt2 = 0; kt2 < 2; ++kt2)
; #pragma unroll
;     for (int e = 0; e < 16; ++e) {
;       const float sv = mask(kt2 * 32 + crow(e, hh)) ? S[kt2][e] : -1e30f;
;       S[kt2][e] = sv; mx = fmaxf(mx, sv);
;     }
;   softmax_finish<HAS_O>(S, mx, 0.f, m, l, O);
; }
	v_or_b32_e32 v80, s12, v165
	v_cndmask_b32_e32 v98, v185, v50, vcc
	v_cmp_le_i32_e32 vcc, v80, v148
	v_cmp_gt_i32_e64 s[0:1], v80, v160
	s_and_b64 vcc, vcc, s[0:1]
	v_or_b32_e32 v80, 40, v0
	v_cndmask_b32_e32 v99, v185, v51, vcc
	v_cmp_le_i32_e32 vcc, v80, v148
	v_cmp_gt_i32_e64 s[0:1], v80, v160
	s_and_b64 vcc, vcc, s[0:1]
	v_or_b32_e32 v80, 41, v0
	v_cndmask_b32_e32 v100, v185, v52, vcc
	v_cmp_le_i32_e32 vcc, v80, v148
	v_cmp_gt_i32_e64 s[0:1], v80, v160
	s_and_b64 vcc, vcc, s[0:1]
	v_or_b32_e32 v80, 42, v0
	v_cndmask_b32_e32 v101, v185, v53, vcc
	v_cmp_le_i32_e32 vcc, v80, v148
	v_cmp_gt_i32_e64 s[0:1], v80, v160
	s_and_b64 vcc, vcc, s[0:1]
	v_or_b32_e32 v80, 43, v0
	v_cndmask_b32_e32 v102, v185, v54, vcc
	v_cmp_le_i32_e32 vcc, v80, v148
	v_cmp_gt_i32_e64 s[0:1], v80, v160
	s_and_b64 vcc, vcc, s[0:1]
	v_or_b32_e32 v80, 48, v0
	v_cndmask_b32_e32 v103, v185, v55, vcc
	v_cmp_le_i32_e32 vcc, v80, v148
	v_cmp_gt_i32_e64 s[0:1], v80, v160
	s_and_b64 vcc, vcc, s[0:1]
	v_or_b32_e32 v80, 49, v0
	v_max3_f32 v4, v2, s97, v3
	v_cndmask_b32_e32 v104, v185, v56, vcc
	v_cmp_le_i32_e32 vcc, v80, v148
	v_cmp_gt_i32_e64 s[0:1], v80, v160
	v_max3_f32 v4, v4, v5, v6
	s_and_b64 vcc, vcc, s[0:1]
	v_or_b32_e32 v80, 50, v0
	v_max3_f32 v4, v4, v7, v8
	v_cndmask_b32_e32 v105, v185, v57, vcc
	v_cmp_le_i32_e32 vcc, v80, v148
	v_cmp_gt_i32_e64 s[0:1], v80, v160
	v_max3_f32 v4, v4, v9, v10
	s_and_b64 vcc, vcc, s[0:1]
	v_or_b32_e32 v80, 51, v0
	v_max3_f32 v4, v4, v11, v12
	v_cndmask_b32_e32 v106, v185, v58, vcc
	v_cmp_le_i32_e32 vcc, v80, v148
	v_cmp_gt_i32_e64 s[0:1], v80, v160
	v_max3_f32 v4, v4, v13, v14
	s_and_b64 vcc, vcc, s[0:1]
	v_or_b32_e32 v80, 56, v0
	v_max3_f32 v4, v4, v15, v93
	v_cndmask_b32_e32 v107, v185, v59, vcc
	v_cmp_le_i32_e32 vcc, v80, v148
	v_cmp_gt_i32_e64 s[0:1], v80, v160
	v_max3_f32 v4, v4, v94, v95
	s_and_b64 vcc, vcc, s[0:1]
	v_or_b32_e32 v80, 57, v0
	v_max3_f32 v4, v4, v96, v97
	v_cndmask_b32_e32 v108, v185, v60, vcc
	v_cmp_le_i32_e32 vcc, v80, v148
	v_cmp_gt_i32_e64 s[0:1], v80, v160
	v_max3_f32 v4, v4, v98, v99
	s_and_b64 vcc, vcc, s[0:1]
	v_or_b32_e32 v80, 58, v0
	v_max3_f32 v4, v4, v100, v101
	v_cndmask_b32_e32 v109, v185, v61, vcc
	v_cmp_le_i32_e32 vcc, v80, v148
	v_cmp_gt_i32_e64 s[0:1], v80, v160
	v_max3_f32 v4, v4, v102, v103
	s_and_b64 vcc, vcc, s[0:1]
	v_or_b32_e32 v0, 59, v0
	v_max3_f32 v4, v4, v104, v105
	v_cndmask_b32_e32 v110, v185, v62, vcc
	v_cmp_le_i32_e32 vcc, v0, v148
	v_cmp_gt_i32_e64 s[0:1], v0, v160
	v_max3_f32 v4, v4, v106, v107
	s_and_b64 vcc, vcc, s[0:1]
	v_max3_f32 v4, v4, v108, v109
	v_cndmask_b32_e32 v0, v185, v63, vcc
	v_max3_f32 v4, v4, v110, v0
	v_mov_b32_e32 v80, v4
	s_nop 1
	v_permlane32_swap_b32_e32 v4, v80
	v_max_f32_e32 v80, v80, v80
	v_max_f32_e32 v4, v4, v4
	v_max_f32_e32 v4, v4, v80
	v_add_f32_e32 v80, 0x41000000, v208
	v_cmp_gt_f32_e32 vcc, v4, v80
	s_nop 1
	v_cndmask_b32_e32 v209, v208, v4, vcc
	v_add_f32_e32 v4, 0, v209
	v_sub_f32_e32 v2, v2, v4
	v_exp_f32_e32 v80, v2
	v_sub_f32_e32 v3, v3, v4
	v_exp_f32_e32 v81, v3
	v_sub_f32_e32 v3, v5, v4
	v_exp_f32_e32 v82, v3
	v_sub_f32_e32 v3, v6, v4
	v_exp_f32_e32 v83, v3
	v_sub_f32_e32 v3, v7, v4
	v_add_f32_e32 v85, 0, v80
	v_exp_f32_e32 v84, v3
	v_sub_f32_e32 v5, v8, v4
	v_add_f32_e32 v3, v81, v85
	v_exp_f32_e32 v85, v5
	v_sub_f32_e32 v5, v9, v4
	v_add_f32_e32 v3, v82, v3
	v_exp_f32_e32 v86, v5
	v_sub_f32_e32 v5, v10, v4
	v_add_f32_e32 v3, v83, v3
	v_exp_f32_e32 v87, v5
	v_sub_f32_e32 v5, v11, v4
	v_add_f32_e32 v3, v84, v3
	v_exp_f32_e32 v88, v5
	v_sub_f32_e32 v5, v12, v4
	v_add_f32_e32 v3, v85, v3
	v_exp_f32_e32 v89, v5
	v_sub_f32_e32 v5, v13, v4
	v_add_f32_e32 v3, v86, v3
	v_exp_f32_e32 v90, v5
	v_sub_f32_e32 v5, v14, v4
	v_add_f32_e32 v3, v87, v3
	v_exp_f32_e32 v91, v5
	v_sub_f32_e32 v5, v15, v4
	v_add_f32_e32 v3, v88, v3
	v_exp_f32_e32 v92, v5
	v_sub_f32_e32 v5, v93, v4
	v_add_f32_e32 v3, v89, v3
	v_exp_f32_e32 v93, v5
	v_sub_f32_e32 v5, v94, v4
	v_add_f32_e32 v3, v90, v3
	v_exp_f32_e32 v94, v5
	v_sub_f32_e32 v5, v95, v4
	v_add_f32_e32 v3, v91, v3
	v_exp_f32_e32 v95, v5
	v_sub_f32_e32 v5, v96, v4
	v_add_f32_e32 v3, v92, v3
	v_exp_f32_e32 v96, v5
	v_sub_f32_e32 v5, v97, v4
	v_add_f32_e32 v3, v93, v3
	v_exp_f32_e32 v97, v5
	v_sub_f32_e32 v5, v98, v4
	v_add_f32_e32 v3, v94, v3
	v_exp_f32_e32 v98, v5
	v_sub_f32_e32 v5, v99, v4
	v_add_f32_e32 v3, v95, v3
	v_exp_f32_e32 v99, v5
	v_sub_f32_e32 v5, v100, v4
	v_add_f32_e32 v3, v96, v3
	v_exp_f32_e32 v100, v5
	v_sub_f32_e32 v5, v101, v4
	v_add_f32_e32 v3, v97, v3
	v_exp_f32_e32 v101, v5
	v_sub_f32_e32 v5, v102, v4
	v_add_f32_e32 v3, v98, v3
	v_exp_f32_e32 v102, v5
	v_sub_f32_e32 v5, v103, v4
	v_add_f32_e32 v3, v99, v3
	v_exp_f32_e32 v103, v5
	v_sub_f32_e32 v5, v104, v4
	v_add_f32_e32 v3, v100, v3
	v_exp_f32_e32 v104, v5
	v_sub_f32_e32 v5, v105, v4
	v_add_f32_e32 v3, v101, v3
	v_exp_f32_e32 v105, v5
	v_sub_f32_e32 v5, v106, v4
	v_add_f32_e32 v3, v102, v3
	v_exp_f32_e32 v106, v5
	v_sub_f32_e32 v5, v107, v4
	v_add_f32_e32 v3, v103, v3
	v_exp_f32_e32 v107, v5
	v_sub_f32_e32 v5, v108, v4
	v_add_f32_e32 v3, v104, v3
	v_exp_f32_e32 v108, v5
	v_sub_f32_e32 v5, v109, v4
	v_sub_f32_e32 v2, v208, v209
	v_add_f32_e32 v3, v105, v3
	v_exp_f32_e32 v109, v5
	v_sub_f32_e32 v5, v110, v4
	v_sub_f32_e32 v0, v0, v4
	v_add_f32_e32 v3, v106, v3
	v_exp_f32_e32 v110, v5
	v_exp_f32_e32 v111, v0
	v_exp_f32_e32 v0, v2
	v_add_f32_e32 v3, v107, v3
	v_add_f32_e32 v3, v108, v3
	v_add_f32_e32 v2, v109, v3
	v_add_f32_e32 v2, v110, v2
	v_cmp_neq_f32_e32 vcc, 1.0, v0
	v_add_f32_e32 v213, v111, v2
	s_cmp_lg_u64 vcc, 0
	v_fmac_f32_e32 v213, v149, v0
	s_cselect_b64 s[0:1], -1, 0
	s_cbranch_execz .LBB0_950
	s_branch .LBB0_951
